# attention loop: the two workgroups sharing a CU swap issue priority every four trips (complementary s_setprio), so neither is the permanent arbitration loser
# speedup vs baseline: 1.0149x; 1.0092x over previous
.LBB0_350:
	s_lshl_b32 s0, s2, 14
	s_add_u32 s76, s94, s0
	s_addc_u32 s77, s95, 0
	s_add_u32 s76, s76, 0x6bc0000
	s_addc_u32 s77, s77, 0
	s_lshr_b32 s0, s2, 7
	s_mul_i32 s0, s0, 0x108000
	s_add_u32 s78, s94, s0
	s_addc_u32 s79, s95, 0
	s_add_u32 s78, s78, 0x7400000
	s_addc_u32 s79, s79, 0
	s_add_u32 s80, s78, 0x420000
	s_addc_u32 s81, s79, 0
	v_and_b32_e32 v136, 31, v138
	v_bfe_u32 v137, v138, 5, 1
	v_lshrrev_b32_e32 v167, 6, v138
	v_lshl_add_u32 v171, v167, 5, v136
	v_readfirstlane_b32 s83, v167
	v_lshlrev_b32_e32 v171, 7, v171
	v_lshl_add_u32 v171, v137, 4, v171
	s_lshl_b32 s83, s83, 11
	global_load_dwordx4 v[96:99], v171, s[76:77]
	global_load_dwordx4 v[100:103], v171, s[76:77] offset:32
	global_load_dwordx4 v[104:107], v171, s[76:77] offset:64
	global_load_dwordx4 v[108:111], v171, s[76:77] offset:96
	v_and_b32_e32 v168, 0x13, v136
	v_and_b32_e32 v169, 4, v136
	v_lshl_or_b32 v168, v169, 1, v168
	v_and_b32_e32 v169, 8, v136
	v_lshrrev_b32_e32 v169, 1, v169
	v_or_b32_e32 v168, v168, v169
	v_bfe_u32 v170, v168, 1, 3
	v_xor_b32_e32 v170, v170, v137
	v_lshlrev_b32_e32 v170, 4, v170
	v_lshlrev_b32_e32 v168, 7, v168
	v_add_u32_e32 v244, v168, v170
	v_xor_b32_e32 v169, 32, v170
	v_add_u32_e32 v245, v168, v169
	v_xor_b32_e32 v169, 64, v170
	v_add_u32_e32 v246, v168, v169
	v_xor_b32_e32 v169, 96, v170
	v_add_u32_e32 v247, v168, v169
	v_bfe_u32 v170, v136, 1, 3
	v_xor_b32_e32 v170, v170, v137
	v_lshlrev_b32_e32 v170, 4, v170
	v_lshlrev_b32_e32 v168, 7, v136
	v_add_u32_e32 v248, v168, v170
	v_xor_b32_e32 v169, 32, v170
	v_add_u32_e32 v249, v168, v169
	v_xor_b32_e32 v169, 64, v170
	v_add_u32_e32 v250, v168, v169
	v_xor_b32_e32 v169, 96, v170
	v_add_u32_e32 v251, v168, v169
	v_bfe_u32 v168, v138, 3, 3
	v_and_b32_e32 v169, 7, v138
	v_lshrrev_b32_e32 v170, 1, v168
	v_xor_b32_e32 v170, v170, v169
	v_lshl_add_u32 v171, v167, 4, v168
	v_lshlrev_b32_e32 v169, 7, v171
	v_lshl_add_u32 v252, v170, 4, v169
	v_xor_b32_e32 v168, 4, v170
	v_lshl_add_u32 v253, v168, 4, v169
	s_movk_i32 s0, 0x4200
	v_mul_lo_u32 v169, v171, s0
	v_lshl_add_u32 v254, v170, 4, v169
	v_lshl_add_u32 v255, v168, 4, v169
	v_add_u32_e32 v255, 134144, v255
	s_barrier
	s_add_i32 m0, s83, 0
	s_nop 0
	global_load_lds_dwordx4 v252, s[78:79]
	global_load_lds_dwordx4 v253, s[78:79] offset:1024
	s_add_i32 m0, s83, 8192
	s_nop 0
	global_load_lds_dwordx4 v254, s[80:81]
	global_load_lds_dwordx4 v255, s[80:81] offset:1024
	s_add_u32 s78, s78, 0x2000
	s_addc_u32 s79, s79, 0
	s_add_u32 s80, s80, 0x80
	s_addc_u32 s81, s81, 0
	s_add_i32 m0, s83, 16384
	s_nop 0
	global_load_lds_dwordx4 v252, s[78:79]
	global_load_lds_dwordx4 v253, s[78:79] offset:1024
	s_add_i32 m0, s83, 24576
	s_nop 0
	global_load_lds_dwordx4 v254, s[80:81]
	global_load_lds_dwordx4 v255, s[80:81] offset:1024
	s_add_u32 s78, s78, 0x2000
	s_addc_u32 s79, s79, 0
	s_add_u32 s80, s80, 0x80
	s_addc_u32 s81, s81, 0
	v_mov_b32_e32 v32, 0
	v_mov_b32_e32 v33, 0
	v_mov_b32_e32 v34, 0
	v_mov_b32_e32 v35, 0
	v_mov_b32_e32 v36, 0
	v_mov_b32_e32 v37, 0
	v_mov_b32_e32 v38, 0
	v_mov_b32_e32 v39, 0
	v_mov_b32_e32 v40, 0
	v_mov_b32_e32 v41, 0
	v_mov_b32_e32 v42, 0
	v_mov_b32_e32 v43, 0
	v_mov_b32_e32 v44, 0
	v_mov_b32_e32 v45, 0
	v_mov_b32_e32 v46, 0
	v_mov_b32_e32 v47, 0
	v_mov_b32_e32 v48, 0
	v_mov_b32_e32 v49, 0
	v_mov_b32_e32 v50, 0
	v_mov_b32_e32 v51, 0
	v_mov_b32_e32 v52, 0
	v_mov_b32_e32 v53, 0
	v_mov_b32_e32 v54, 0
	v_mov_b32_e32 v55, 0
	v_mov_b32_e32 v56, 0
	v_mov_b32_e32 v57, 0
	v_mov_b32_e32 v58, 0
	v_mov_b32_e32 v59, 0
	v_mov_b32_e32 v60, 0
	v_mov_b32_e32 v61, 0
	v_mov_b32_e32 v62, 0
	v_mov_b32_e32 v63, 0
	v_mov_b32_e32 v80, 0
	v_mov_b32_e32 v81, 0
	v_mov_b32_e32 v82, 0
	v_mov_b32_e32 v83, 0
	v_mov_b32_e32 v84, 0
	v_mov_b32_e32 v85, 0
	v_mov_b32_e32 v86, 0
	v_mov_b32_e32 v87, 0
	v_mov_b32_e32 v88, 0
	v_mov_b32_e32 v89, 0
	v_mov_b32_e32 v90, 0
	v_mov_b32_e32 v91, 0
	v_mov_b32_e32 v92, 0
	v_mov_b32_e32 v93, 0
	v_mov_b32_e32 v94, 0
	v_mov_b32_e32 v95, 0
	v_mov_b32_e32 v192, 0
	v_mov_b32_e32 v193, 0
	v_mov_b32_e32 v194, 0
	v_mov_b32_e32 v195, 0
	v_mov_b32_e32 v196, 0
	v_mov_b32_e32 v197, 0
	v_mov_b32_e32 v198, 0
	v_mov_b32_e32 v199, 0
	v_mov_b32_e32 v200, 0
	v_mov_b32_e32 v201, 0
	v_mov_b32_e32 v202, 0
	v_mov_b32_e32 v203, 0
	v_mov_b32_e32 v240, 0
	v_mov_b32_e32 v241, 0
	v_mov_b32_e32 v242, 0
	v_mov_b32_e32 v243, 0
	v_mov_b32_e32 v128, 0
	v_mov_b32_e32 v129, 0
	s_mov_b32 s84, 0
	s_getreg_b32 s85, hwreg(HW_REG_LDS_ALLOC, 0, 8)
	s_cmp_lg_u32 s85, 0
	s_cselect_b32 s85, 4, 0
	s_mov_b32 s82, 33
	s_waitcnt vmcnt(0)
	s_barrier
	ds_read_b128 v[208:211], v244 offset:0
	ds_read_b128 v[212:215], v245 offset:0
	ds_read_b128 v[216:219], v246 offset:0
	ds_read_b128 v[220:223], v247 offset:0
	ds_read_b128 v[224:227], v244 offset:4096
	ds_read_b128 v[228:231], v245 offset:4096
	ds_read_b128 v[232:235], v246 offset:4096
	ds_read_b128 v[236:239], v247 offset:4096
	s_waitcnt lgkmcnt(7)
	v_mfma_f32_32x32x16_bf16 v[0:15], v[208:211], v[96:99], 0
	s_waitcnt lgkmcnt(6)
	v_mfma_f32_32x32x16_bf16 v[0:15], v[212:215], v[100:103], v[0:15]
	s_waitcnt lgkmcnt(5)
	v_mfma_f32_32x32x16_bf16 v[0:15], v[216:219], v[104:107], v[0:15]
	s_waitcnt lgkmcnt(4)
	v_mfma_f32_32x32x16_bf16 v[0:15], v[220:223], v[108:111], v[0:15]
	s_waitcnt lgkmcnt(0)
.Lat_loop:
	s_add_u32 s85, s85, 1
	s_bitcmp1_b32 s85, 2
	s_cbranch_scc1 .Lat_prhi
	s_setprio 0
	s_branch .Lat_prdone
.Lat_prhi:
	s_setprio 1

.Lat_rare7_ret:
	v_add_f32_e32 v128, v128, v134
	s_waitcnt vmcnt(0)
	s_barrier
	s_sub_u32 s82, s82, 1
	s_cmp_lg_u32 s82, 0
	s_cbranch_scc1 .Lat_loop
	s_setprio 0
	v_cvt_pk_bf16_f32 v112, v80, v81
	v_cvt_pk_bf16_f32 v113, v82, v83
	v_cvt_pk_bf16_f32 v114, v84, v85
	v_cvt_pk_bf16_f32 v115, v86, v87
	v_cvt_pk_bf16_f32 v116, v88, v89
	v_cvt_pk_bf16_f32 v117, v90, v91
	v_cvt_pk_bf16_f32 v118, v92, v93
	v_cvt_pk_bf16_f32 v119, v94, v95
	s_waitcnt lgkmcnt(0)
	v_mfma_f32_32x32x16_bf16 v[32:47], v[192:195], v[112:115], v[32:47]
	v_mfma_f32_32x32x16_bf16 v[48:63], v[196:199], v[112:115], v[48:63]
	v_mfma_f32_32x32x16_bf16 v[32:47], v[200:203], v[116:119], v[32:47]
	v_mfma_f32_32x32x16_bf16 v[48:63], v[240:243], v[116:119], v[48:63]
	s_nop 7
	s_nop 7
	s_waitcnt vmcnt(0)
	s_lshr_b32 s0, s2, 8
	s_lshl_b32 s0, s0, 13
	s_and_b32 s1, s2, 63
	s_lshl_b32 s1, s1, 7
	s_or_b32 s0, s0, s1
	s_bfe_u32 s1, s2, 0x20006
	s_lshl_b32 s1, s1, 7
	s_add_u32 s86, s94, 0x3200000
	s_addc_u32 s87, s95, 0
	s_add_u32 s88, s94, 0x1100200
	s_addc_u32 s89, s95, 0
	v_lshrrev_b32_e32 v0, 1, v138
	v_and_b32_e32 v0, 0xe0, v0
	v_and_or_b32 v0, v138, 31, v0
	v_add_u32_e32 v0, s0, v0
	v_bfe_u32 v3, v138, 5, 1
	v_lshl_add_u32 v3, v3, 3, s1
	v_mul_lo_u32 v1, v0, s64
	v_add_u32_e32 v1, v1, v3
	v_lshl_add_u32 v2, v0, 11, v3
	global_load_dwordx2 v[64:65], v1, s[86:87]
	global_load_dwordx2 v[66:67], v1, s[86:87] offset:16
	global_load_dwordx2 v[68:69], v1, s[86:87] offset:32
	global_load_dwordx2 v[70:71], v1, s[86:87] offset:48
	global_load_dwordx2 v[72:73], v1, s[86:87] offset:64
	global_load_dwordx2 v[74:75], v1, s[86:87] offset:80
	global_load_dwordx2 v[76:77], v1, s[86:87] offset:96
	global_load_dwordx2 v[78:79], v1, s[86:87] offset:112
	v_mbcnt_lo_u32_b32 v4, -1, 0
	v_mbcnt_hi_u32_b32 v4, -1, v4
	v_xor_b32_e32 v4, 32, v4
	v_lshlrev_b32_e32 v4, 2, v4
	ds_bpermute_b32 v5, v4, v128
	s_waitcnt lgkmcnt(0)
	v_add_f32_e32 v5, v128, v5
	v_mov_b32_e32 v7, 1.0
	v_div_scale_f32 v8, s[0:1], v5, v5, v7
	v_rcp_f32_e32 v9, v8
	s_nop 0
	v_fma_f32 v10, -v8, v9, 1.0
	v_fmac_f32_e32 v9, v10, v9
	v_div_scale_f32 v10, vcc, v7, v5, v7
	v_mul_f32_e32 v11, v10, v9
	v_fma_f32 v12, -v8, v11, v10
	v_fmac_f32_e32 v11, v12, v9
	v_fma_f32 v8, -v8, v11, v10
	v_div_fmas_f32 v8, v8, v9, v11
	v_div_fixup_f32 v6, v8, v5, v7
	s_waitcnt vmcnt(7)
	v_lshlrev_b32_e32 v16, 16, v64
	v_and_b32_e32 v17, 0xffff0000, v64
	v_lshlrev_b32_e32 v18, 16, v65
	v_and_b32_e32 v19, 0xffff0000, v65
	v_mul_f32_e32 v20, 0xbfb8aa3b, v16
	v_mul_f32_e32 v21, 0xbfb8aa3b, v17
	v_mul_f32_e32 v22, 0xbfb8aa3b, v18
	v_mul_f32_e32 v23, 0xbfb8aa3b, v19
	v_exp_f32_e32 v20, v20
	v_exp_f32_e32 v21, v21
	v_exp_f32_e32 v22, v22
	v_exp_f32_e32 v23, v23
	s_nop 0
	v_add_f32_e32 v20, 1.0, v20
	v_add_f32_e32 v21, 1.0, v21
	v_add_f32_e32 v22, 1.0, v22
	v_add_f32_e32 v23, 1.0, v23
	v_div_scale_f32 v8, s[0:1], v20, v20, v16
	v_rcp_f32_e32 v9, v8
	s_nop 0
	v_fma_f32 v10, -v8, v9, 1.0
	v_fmac_f32_e32 v9, v10, v9
	v_div_scale_f32 v10, vcc, v16, v20, v16
	v_mul_f32_e32 v11, v10, v9
	v_fma_f32 v12, -v8, v11, v10
	v_fmac_f32_e32 v11, v12, v9
	v_fma_f32 v8, -v8, v11, v10
	v_div_fmas_f32 v8, v8, v9, v11
	v_div_fixup_f32 v24, v8, v20, v16
	v_div_scale_f32 v8, s[0:1], v21, v21, v17
	v_rcp_f32_e32 v9, v8
	s_nop 0
	v_fma_f32 v10, -v8, v9, 1.0
	v_fmac_f32_e32 v9, v10, v9
	v_div_scale_f32 v10, vcc, v17, v21, v17
	v_mul_f32_e32 v11, v10, v9
	v_fma_f32 v12, -v8, v11, v10
	v_fmac_f32_e32 v11, v12, v9
	v_fma_f32 v8, -v8, v11, v10
	v_div_fmas_f32 v8, v8, v9, v11
	v_div_fixup_f32 v25, v8, v21, v17
	v_div_scale_f32 v8, s[0:1], v22, v22, v18
	v_rcp_f32_e32 v9, v8
	s_nop 0
	v_fma_f32 v10, -v8, v9, 1.0
	v_fmac_f32_e32 v9, v10, v9
	v_div_scale_f32 v10, vcc, v18, v22, v18
	v_mul_f32_e32 v11, v10, v9
	v_fma_f32 v12, -v8, v11, v10
	v_fmac_f32_e32 v11, v12, v9
	v_fma_f32 v8, -v8, v11, v10
	v_div_fmas_f32 v8, v8, v9, v11
	v_div_fixup_f32 v26, v8, v22, v18
	v_div_scale_f32 v8, s[0:1], v23, v23, v19
	v_rcp_f32_e32 v9, v8
	s_nop 0
	v_fma_f32 v10, -v8, v9, 1.0
	v_fmac_f32_e32 v9, v10, v9
	v_div_scale_f32 v10, vcc, v19, v23, v19
	v_mul_f32_e32 v11, v10, v9
	v_fma_f32 v12, -v8, v11, v10
	v_fmac_f32_e32 v11, v12, v9
	v_fma_f32 v8, -v8, v11, v10
	v_div_fmas_f32 v8, v8, v9, v11
	v_div_fixup_f32 v27, v8, v23, v19
	v_mul_f32_e32 v24, v24, v32
	v_mul_f32_e32 v25, v25, v33
	v_mul_f32_e32 v26, v26, v34
	v_mul_f32_e32 v27, v27, v35
	v_mul_f32_e32 v24, v24, v6
	v_mul_f32_e32 v25, v25, v6
	v_mul_f32_e32 v26, v26, v6
	v_mul_f32_e32 v27, v27, v6
	v_cvt_pk_bf16_f32 v28, v24, v25
	v_cvt_pk_bf16_f32 v29, v26, v27
	global_store_dwordx2 v2, v[28:29], s[88:89]
	s_waitcnt vmcnt(7)
	v_lshlrev_b32_e32 v16, 16, v66
	v_and_b32_e32 v17, 0xffff0000, v66
	v_lshlrev_b32_e32 v18, 16, v67
	v_and_b32_e32 v19, 0xffff0000, v67
	v_mul_f32_e32 v20, 0xbfb8aa3b, v16
	v_mul_f32_e32 v21, 0xbfb8aa3b, v17
	v_mul_f32_e32 v22, 0xbfb8aa3b, v18
	v_mul_f32_e32 v23, 0xbfb8aa3b, v19
	v_exp_f32_e32 v20, v20
	v_exp_f32_e32 v21, v21
	v_exp_f32_e32 v22, v22
	v_exp_f32_e32 v23, v23
	s_nop 0
	v_add_f32_e32 v20, 1.0, v20
	v_add_f32_e32 v21, 1.0, v21
	v_add_f32_e32 v22, 1.0, v22
	v_add_f32_e32 v23, 1.0, v23
	v_div_scale_f32 v8, s[0:1], v20, v20, v16
	v_rcp_f32_e32 v9, v8
	s_nop 0
	v_fma_f32 v10, -v8, v9, 1.0
	v_fmac_f32_e32 v9, v10, v9
	v_div_scale_f32 v10, vcc, v16, v20, v16
	v_mul_f32_e32 v11, v10, v9
	v_fma_f32 v12, -v8, v11, v10
	v_fmac_f32_e32 v11, v12, v9
	v_fma_f32 v8, -v8, v11, v10
	v_div_fmas_f32 v8, v8, v9, v11
	v_div_fixup_f32 v24, v8, v20, v16
	v_div_scale_f32 v8, s[0:1], v21, v21, v17
	v_rcp_f32_e32 v9, v8
	s_nop 0
	v_fma_f32 v10, -v8, v9, 1.0
	v_fmac_f32_e32 v9, v10, v9
	v_div_scale_f32 v10, vcc, v17, v21, v17
	v_mul_f32_e32 v11, v10, v9
	v_fma_f32 v12, -v8, v11, v10
	v_fmac_f32_e32 v11, v12, v9
	v_fma_f32 v8, -v8, v11, v10
	v_div_fmas_f32 v8, v8, v9, v11
	v_div_fixup_f32 v25, v8, v21, v17
	v_div_scale_f32 v8, s[0:1], v22, v22, v18
	v_rcp_f32_e32 v9, v8
	s_nop 0
	v_fma_f32 v10, -v8, v9, 1.0
	v_fmac_f32_e32 v9, v10, v9
	v_div_scale_f32 v10, vcc, v18, v22, v18
	v_mul_f32_e32 v11, v10, v9
	v_fma_f32 v12, -v8, v11, v10
	v_fmac_f32_e32 v11, v12, v9
	v_fma_f32 v8, -v8, v11, v10
	v_div_fmas_f32 v8, v8, v9, v11
	v_div_fixup_f32 v26, v8, v22, v18
	v_div_scale_f32 v8, s[0:1], v23, v23, v19
	v_rcp_f32_e32 v9, v8
	s_nop 0
	v_fma_f32 v10, -v8, v9, 1.0
	v_fmac_f32_e32 v9, v10, v9
	v_div_scale_f32 v10, vcc, v19, v23, v19
	v_mul_f32_e32 v11, v10, v9
	v_fma_f32 v12, -v8, v11, v10
	v_fmac_f32_e32 v11, v12, v9
	v_fma_f32 v8, -v8, v11, v10
	v_div_fmas_f32 v8, v8, v9, v11
	v_div_fixup_f32 v27, v8, v23, v19
	v_mul_f32_e32 v24, v24, v36
	v_mul_f32_e32 v25, v25, v37
	v_mul_f32_e32 v26, v26, v38
	v_mul_f32_e32 v27, v27, v39
	v_mul_f32_e32 v24, v24, v6
	v_mul_f32_e32 v25, v25, v6
	v_mul_f32_e32 v26, v26, v6
	v_mul_f32_e32 v27, v27, v6
	v_cvt_pk_bf16_f32 v30, v24, v25
	v_cvt_pk_bf16_f32 v31, v26, v27
	global_store_dwordx2 v2, v[30:31], s[88:89] offset:16
	s_waitcnt vmcnt(7)
	v_lshlrev_b32_e32 v16, 16, v68
	v_and_b32_e32 v17, 0xffff0000, v68
	v_lshlrev_b32_e32 v18, 16, v69
	v_and_b32_e32 v19, 0xffff0000, v69
	v_mul_f32_e32 v20, 0xbfb8aa3b, v16
	v_mul_f32_e32 v21, 0xbfb8aa3b, v17
	v_mul_f32_e32 v22, 0xbfb8aa3b, v18
	v_mul_f32_e32 v23, 0xbfb8aa3b, v19
	v_exp_f32_e32 v20, v20
	v_exp_f32_e32 v21, v21
	v_exp_f32_e32 v22, v22
	v_exp_f32_e32 v23, v23
	s_nop 0
	v_add_f32_e32 v20, 1.0, v20
	v_add_f32_e32 v21, 1.0, v21
	v_add_f32_e32 v22, 1.0, v22
	v_add_f32_e32 v23, 1.0, v23
	v_div_scale_f32 v8, s[0:1], v20, v20, v16
	v_rcp_f32_e32 v9, v8
	s_nop 0
	v_fma_f32 v10, -v8, v9, 1.0
	v_fmac_f32_e32 v9, v10, v9
	v_div_scale_f32 v10, vcc, v16, v20, v16
	v_mul_f32_e32 v11, v10, v9
	v_fma_f32 v12, -v8, v11, v10
	v_fmac_f32_e32 v11, v12, v9
	v_fma_f32 v8, -v8, v11, v10
	v_div_fmas_f32 v8, v8, v9, v11
	v_div_fixup_f32 v24, v8, v20, v16
	v_div_scale_f32 v8, s[0:1], v21, v21, v17
	v_rcp_f32_e32 v9, v8
	s_nop 0
	v_fma_f32 v10, -v8, v9, 1.0
	v_fmac_f32_e32 v9, v10, v9
	v_div_scale_f32 v10, vcc, v17, v21, v17
	v_mul_f32_e32 v11, v10, v9
	v_fma_f32 v12, -v8, v11, v10
	v_fmac_f32_e32 v11, v12, v9
	v_fma_f32 v8, -v8, v11, v10
	v_div_fmas_f32 v8, v8, v9, v11
	v_div_fixup_f32 v25, v8, v21, v17
	v_div_scale_f32 v8, s[0:1], v22, v22, v18
	v_rcp_f32_e32 v9, v8
	s_nop 0
	v_fma_f32 v10, -v8, v9, 1.0
	v_fmac_f32_e32 v9, v10, v9
	v_div_scale_f32 v10, vcc, v18, v22, v18
	v_mul_f32_e32 v11, v10, v9
	v_fma_f32 v12, -v8, v11, v10
	v_fmac_f32_e32 v11, v12, v9
	v_fma_f32 v8, -v8, v11, v10
	v_div_fmas_f32 v8, v8, v9, v11
	v_div_fixup_f32 v26, v8, v22, v18
	v_div_scale_f32 v8, s[0:1], v23, v23, v19
	v_rcp_f32_e32 v9, v8
	s_nop 0
	v_fma_f32 v10, -v8, v9, 1.0
	v_fmac_f32_e32 v9, v10, v9
	v_div_scale_f32 v10, vcc, v19, v23, v19
	v_mul_f32_e32 v11, v10, v9
	v_fma_f32 v12, -v8, v11, v10
	v_fmac_f32_e32 v11, v12, v9
	v_fma_f32 v8, -v8, v11, v10
	v_div_fmas_f32 v8, v8, v9, v11
	v_div_fixup_f32 v27, v8, v23, v19
	v_mul_f32_e32 v24, v24, v40
	v_mul_f32_e32 v25, v25, v41
	v_mul_f32_e32 v26, v26, v42
	v_mul_f32_e32 v27, v27, v43
	v_mul_f32_e32 v24, v24, v6
	v_mul_f32_e32 v25, v25, v6
	v_mul_f32_e32 v26, v26, v6
	v_mul_f32_e32 v27, v27, v6
	v_cvt_pk_bf16_f32 v28, v24, v25
	v_cvt_pk_bf16_f32 v29, v26, v27
	global_store_dwordx2 v2, v[28:29], s[88:89] offset:32
	s_waitcnt vmcnt(7)
	v_lshlrev_b32_e32 v16, 16, v70
	v_and_b32_e32 v17, 0xffff0000, v70
	v_lshlrev_b32_e32 v18, 16, v71
	v_and_b32_e32 v19, 0xffff0000, v71
	v_mul_f32_e32 v20, 0xbfb8aa3b, v16
	v_mul_f32_e32 v21, 0xbfb8aa3b, v17
	v_mul_f32_e32 v22, 0xbfb8aa3b, v18
	v_mul_f32_e32 v23, 0xbfb8aa3b, v19
	v_exp_f32_e32 v20, v20
	v_exp_f32_e32 v21, v21
	v_exp_f32_e32 v22, v22
	v_exp_f32_e32 v23, v23
	s_nop 0
	v_add_f32_e32 v20, 1.0, v20
	v_add_f32_e32 v21, 1.0, v21
	v_add_f32_e32 v22, 1.0, v22
	v_add_f32_e32 v23, 1.0, v23
	v_div_scale_f32 v8, s[0:1], v20, v20, v16
	v_rcp_f32_e32 v9, v8
	s_nop 0
	v_fma_f32 v10, -v8, v9, 1.0
	v_fmac_f32_e32 v9, v10, v9
	v_div_scale_f32 v10, vcc, v16, v20, v16
	v_mul_f32_e32 v11, v10, v9
	v_fma_f32 v12, -v8, v11, v10
	v_fmac_f32_e32 v11, v12, v9
	v_fma_f32 v8, -v8, v11, v10
	v_div_fmas_f32 v8, v8, v9, v11
	v_div_fixup_f32 v24, v8, v20, v16
	v_div_scale_f32 v8, s[0:1], v21, v21, v17
	v_rcp_f32_e32 v9, v8
	s_nop 0
	v_fma_f32 v10, -v8, v9, 1.0
	v_fmac_f32_e32 v9, v10, v9
	v_div_scale_f32 v10, vcc, v17, v21, v17
	v_mul_f32_e32 v11, v10, v9
	v_fma_f32 v12, -v8, v11, v10
	v_fmac_f32_e32 v11, v12, v9
	v_fma_f32 v8, -v8, v11, v10
	v_div_fmas_f32 v8, v8, v9, v11
	v_div_fixup_f32 v25, v8, v21, v17
	v_div_scale_f32 v8, s[0:1], v22, v22, v18
	v_rcp_f32_e32 v9, v8
	s_nop 0
	v_fma_f32 v10, -v8, v9, 1.0
	v_fmac_f32_e32 v9, v10, v9
	v_div_scale_f32 v10, vcc, v18, v22, v18
	v_mul_f32_e32 v11, v10, v9
	v_fma_f32 v12, -v8, v11, v10
	v_fmac_f32_e32 v11, v12, v9
	v_fma_f32 v8, -v8, v11, v10
	v_div_fmas_f32 v8, v8, v9, v11
	v_div_fixup_f32 v26, v8, v22, v18
	v_div_scale_f32 v8, s[0:1], v23, v23, v19
	v_rcp_f32_e32 v9, v8
	s_nop 0
	v_fma_f32 v10, -v8, v9, 1.0
	v_fmac_f32_e32 v9, v10, v9
	v_div_scale_f32 v10, vcc, v19, v23, v19
	v_mul_f32_e32 v11, v10, v9
	v_fma_f32 v12, -v8, v11, v10
	v_fmac_f32_e32 v11, v12, v9
	v_fma_f32 v8, -v8, v11, v10
	v_div_fmas_f32 v8, v8, v9, v11
	v_div_fixup_f32 v27, v8, v23, v19
	v_mul_f32_e32 v24, v24, v44
	v_mul_f32_e32 v25, v25, v45
	v_mul_f32_e32 v26, v26, v46
	v_mul_f32_e32 v27, v27, v47
	v_mul_f32_e32 v24, v24, v6
	v_mul_f32_e32 v25, v25, v6
	v_mul_f32_e32 v26, v26, v6
	v_mul_f32_e32 v27, v27, v6
	v_cvt_pk_bf16_f32 v30, v24, v25
	v_cvt_pk_bf16_f32 v31, v26, v27
	global_store_dwordx2 v2, v[30:31], s[88:89] offset:48
	s_waitcnt vmcnt(7)
	v_lshlrev_b32_e32 v16, 16, v72
	v_and_b32_e32 v17, 0xffff0000, v72
	v_lshlrev_b32_e32 v18, 16, v73
	v_and_b32_e32 v19, 0xffff0000, v73
	v_mul_f32_e32 v20, 0xbfb8aa3b, v16
	v_mul_f32_e32 v21, 0xbfb8aa3b, v17
	v_mul_f32_e32 v22, 0xbfb8aa3b, v18
	v_mul_f32_e32 v23, 0xbfb8aa3b, v19
	v_exp_f32_e32 v20, v20
	v_exp_f32_e32 v21, v21
	v_exp_f32_e32 v22, v22
	v_exp_f32_e32 v23, v23
	s_nop 0
	v_add_f32_e32 v20, 1.0, v20
	v_add_f32_e32 v21, 1.0, v21
	v_add_f32_e32 v22, 1.0, v22
	v_add_f32_e32 v23, 1.0, v23
	v_div_scale_f32 v8, s[0:1], v20, v20, v16
	v_rcp_f32_e32 v9, v8
	s_nop 0
	v_fma_f32 v10, -v8, v9, 1.0
	v_fmac_f32_e32 v9, v10, v9
	v_div_scale_f32 v10, vcc, v16, v20, v16
	v_mul_f32_e32 v11, v10, v9
	v_fma_f32 v12, -v8, v11, v10
	v_fmac_f32_e32 v11, v12, v9
	v_fma_f32 v8, -v8, v11, v10
	v_div_fmas_f32 v8, v8, v9, v11
	v_div_fixup_f32 v24, v8, v20, v16
	v_div_scale_f32 v8, s[0:1], v21, v21, v17
	v_rcp_f32_e32 v9, v8
	s_nop 0
	v_fma_f32 v10, -v8, v9, 1.0
	v_fmac_f32_e32 v9, v10, v9
	v_div_scale_f32 v10, vcc, v17, v21, v17
	v_mul_f32_e32 v11, v10, v9
	v_fma_f32 v12, -v8, v11, v10
	v_fmac_f32_e32 v11, v12, v9
	v_fma_f32 v8, -v8, v11, v10
	v_div_fmas_f32 v8, v8, v9, v11
	v_div_fixup_f32 v25, v8, v21, v17
	v_div_scale_f32 v8, s[0:1], v22, v22, v18
	v_rcp_f32_e32 v9, v8
	s_nop 0
	v_fma_f32 v10, -v8, v9, 1.0
	v_fmac_f32_e32 v9, v10, v9
	v_div_scale_f32 v10, vcc, v18, v22, v18
	v_mul_f32_e32 v11, v10, v9
	v_fma_f32 v12, -v8, v11, v10
	v_fmac_f32_e32 v11, v12, v9
	v_fma_f32 v8, -v8, v11, v10
	v_div_fmas_f32 v8, v8, v9, v11
	v_div_fixup_f32 v26, v8, v22, v18
	v_div_scale_f32 v8, s[0:1], v23, v23, v19
	v_rcp_f32_e32 v9, v8
	s_nop 0
	v_fma_f32 v10, -v8, v9, 1.0
	v_fmac_f32_e32 v9, v10, v9
	v_div_scale_f32 v10, vcc, v19, v23, v19
	v_mul_f32_e32 v11, v10, v9
	v_fma_f32 v12, -v8, v11, v10
	v_fmac_f32_e32 v11, v12, v9
	v_fma_f32 v8, -v8, v11, v10
	v_div_fmas_f32 v8, v8, v9, v11
	v_div_fixup_f32 v27, v8, v23, v19
	v_mul_f32_e32 v24, v24, v48
	v_mul_f32_e32 v25, v25, v49
	v_mul_f32_e32 v26, v26, v50
	v_mul_f32_e32 v27, v27, v51
	v_mul_f32_e32 v24, v24, v6
	v_mul_f32_e32 v25, v25, v6
	v_mul_f32_e32 v26, v26, v6
	v_mul_f32_e32 v27, v27, v6
	v_cvt_pk_bf16_f32 v28, v24, v25
	v_cvt_pk_bf16_f32 v29, v26, v27
	global_store_dwordx2 v2, v[28:29], s[88:89] offset:64
	s_waitcnt vmcnt(7)
	v_lshlrev_b32_e32 v16, 16, v74
	v_and_b32_e32 v17, 0xffff0000, v74
	v_lshlrev_b32_e32 v18, 16, v75
	v_and_b32_e32 v19, 0xffff0000, v75
	v_mul_f32_e32 v20, 0xbfb8aa3b, v16
	v_mul_f32_e32 v21, 0xbfb8aa3b, v17
	v_mul_f32_e32 v22, 0xbfb8aa3b, v18
	v_mul_f32_e32 v23, 0xbfb8aa3b, v19
	v_exp_f32_e32 v20, v20
	v_exp_f32_e32 v21, v21
	v_exp_f32_e32 v22, v22
	v_exp_f32_e32 v23, v23
	s_nop 0
	v_add_f32_e32 v20, 1.0, v20
	v_add_f32_e32 v21, 1.0, v21
	v_add_f32_e32 v22, 1.0, v22
	v_add_f32_e32 v23, 1.0, v23
	v_div_scale_f32 v8, s[0:1], v20, v20, v16
	v_rcp_f32_e32 v9, v8
	s_nop 0
	v_fma_f32 v10, -v8, v9, 1.0
	v_fmac_f32_e32 v9, v10, v9
	v_div_scale_f32 v10, vcc, v16, v20, v16
	v_mul_f32_e32 v11, v10, v9
	v_fma_f32 v12, -v8, v11, v10
	v_fmac_f32_e32 v11, v12, v9
	v_fma_f32 v8, -v8, v11, v10
	v_div_fmas_f32 v8, v8, v9, v11
	v_div_fixup_f32 v24, v8, v20, v16
	v_div_scale_f32 v8, s[0:1], v21, v21, v17
	v_rcp_f32_e32 v9, v8
	s_nop 0
	v_fma_f32 v10, -v8, v9, 1.0
	v_fmac_f32_e32 v9, v10, v9
	v_div_scale_f32 v10, vcc, v17, v21, v17
	v_mul_f32_e32 v11, v10, v9
	v_fma_f32 v12, -v8, v11, v10
	v_fmac_f32_e32 v11, v12, v9
	v_fma_f32 v8, -v8, v11, v10
	v_div_fmas_f32 v8, v8, v9, v11
	v_div_fixup_f32 v25, v8, v21, v17
	v_div_scale_f32 v8, s[0:1], v22, v22, v18
	v_rcp_f32_e32 v9, v8
	s_nop 0
	v_fma_f32 v10, -v8, v9, 1.0
	v_fmac_f32_e32 v9, v10, v9
	v_div_scale_f32 v10, vcc, v18, v22, v18
	v_mul_f32_e32 v11, v10, v9
	v_fma_f32 v12, -v8, v11, v10
	v_fmac_f32_e32 v11, v12, v9
	v_fma_f32 v8, -v8, v11, v10
	v_div_fmas_f32 v8, v8, v9, v11
	v_div_fixup_f32 v26, v8, v22, v18
	v_div_scale_f32 v8, s[0:1], v23, v23, v19
	v_rcp_f32_e32 v9, v8
	s_nop 0
	v_fma_f32 v10, -v8, v9, 1.0
	v_fmac_f32_e32 v9, v10, v9
	v_div_scale_f32 v10, vcc, v19, v23, v19
	v_mul_f32_e32 v11, v10, v9
	v_fma_f32 v12, -v8, v11, v10
	v_fmac_f32_e32 v11, v12, v9
	v_fma_f32 v8, -v8, v11, v10
	v_div_fmas_f32 v8, v8, v9, v11
	v_div_fixup_f32 v27, v8, v23, v19
	v_mul_f32_e32 v24, v24, v52
	v_mul_f32_e32 v25, v25, v53
	v_mul_f32_e32 v26, v26, v54
	v_mul_f32_e32 v27, v27, v55
	v_mul_f32_e32 v24, v24, v6
	v_mul_f32_e32 v25, v25, v6
	v_mul_f32_e32 v26, v26, v6
	v_mul_f32_e32 v27, v27, v6
	v_cvt_pk_bf16_f32 v30, v24, v25
	v_cvt_pk_bf16_f32 v31, v26, v27
	global_store_dwordx2 v2, v[30:31], s[88:89] offset:80
	s_waitcnt vmcnt(7)
	v_lshlrev_b32_e32 v16, 16, v76
	v_and_b32_e32 v17, 0xffff0000, v76
	v_lshlrev_b32_e32 v18, 16, v77
	v_and_b32_e32 v19, 0xffff0000, v77
	v_mul_f32_e32 v20, 0xbfb8aa3b, v16
	v_mul_f32_e32 v21, 0xbfb8aa3b, v17
	v_mul_f32_e32 v22, 0xbfb8aa3b, v18
	v_mul_f32_e32 v23, 0xbfb8aa3b, v19
	v_exp_f32_e32 v20, v20
	v_exp_f32_e32 v21, v21
	v_exp_f32_e32 v22, v22
	v_exp_f32_e32 v23, v23
	s_nop 0
	v_add_f32_e32 v20, 1.0, v20
	v_add_f32_e32 v21, 1.0, v21
	v_add_f32_e32 v22, 1.0, v22
	v_add_f32_e32 v23, 1.0, v23
	v_div_scale_f32 v8, s[0:1], v20, v20, v16
	v_rcp_f32_e32 v9, v8
	s_nop 0
	v_fma_f32 v10, -v8, v9, 1.0
	v_fmac_f32_e32 v9, v10, v9
	v_div_scale_f32 v10, vcc, v16, v20, v16
	v_mul_f32_e32 v11, v10, v9
	v_fma_f32 v12, -v8, v11, v10
	v_fmac_f32_e32 v11, v12, v9
	v_fma_f32 v8, -v8, v11, v10
	v_div_fmas_f32 v8, v8, v9, v11
	v_div_fixup_f32 v24, v8, v20, v16
	v_div_scale_f32 v8, s[0:1], v21, v21, v17
	v_rcp_f32_e32 v9, v8
	s_nop 0
	v_fma_f32 v10, -v8, v9, 1.0
	v_fmac_f32_e32 v9, v10, v9
	v_div_scale_f32 v10, vcc, v17, v21, v17
	v_mul_f32_e32 v11, v10, v9
	v_fma_f32 v12, -v8, v11, v10
	v_fmac_f32_e32 v11, v12, v9
	v_fma_f32 v8, -v8, v11, v10
	v_div_fmas_f32 v8, v8, v9, v11
	v_div_fixup_f32 v25, v8, v21, v17
	v_div_scale_f32 v8, s[0:1], v22, v22, v18
	v_rcp_f32_e32 v9, v8
	s_nop 0
	v_fma_f32 v10, -v8, v9, 1.0
	v_fmac_f32_e32 v9, v10, v9
	v_div_scale_f32 v10, vcc, v18, v22, v18
	v_mul_f32_e32 v11, v10, v9
	v_fma_f32 v12, -v8, v11, v10
	v_fmac_f32_e32 v11, v12, v9
	v_fma_f32 v8, -v8, v11, v10
	v_div_fmas_f32 v8, v8, v9, v11
	v_div_fixup_f32 v26, v8, v22, v18
	v_div_scale_f32 v8, s[0:1], v23, v23, v19
	v_rcp_f32_e32 v9, v8
	s_nop 0
	v_fma_f32 v10, -v8, v9, 1.0
	v_fmac_f32_e32 v9, v10, v9
	v_div_scale_f32 v10, vcc, v19, v23, v19
	v_mul_f32_e32 v11, v10, v9
	v_fma_f32 v12, -v8, v11, v10
	v_fmac_f32_e32 v11, v12, v9
	v_fma_f32 v8, -v8, v11, v10
	v_div_fmas_f32 v8, v8, v9, v11
	v_div_fixup_f32 v27, v8, v23, v19
	v_mul_f32_e32 v24, v24, v56
	v_mul_f32_e32 v25, v25, v57
	v_mul_f32_e32 v26, v26, v58
	v_mul_f32_e32 v27, v27, v59
	v_mul_f32_e32 v24, v24, v6
	v_mul_f32_e32 v25, v25, v6
	v_mul_f32_e32 v26, v26, v6
	v_mul_f32_e32 v27, v27, v6
	v_cvt_pk_bf16_f32 v28, v24, v25
	v_cvt_pk_bf16_f32 v29, v26, v27
	global_store_dwordx2 v2, v[28:29], s[88:89] offset:96
	s_waitcnt vmcnt(7)
	v_lshlrev_b32_e32 v16, 16, v78
	v_and_b32_e32 v17, 0xffff0000, v78
	v_lshlrev_b32_e32 v18, 16, v79
	v_and_b32_e32 v19, 0xffff0000, v79
	v_mul_f32_e32 v20, 0xbfb8aa3b, v16
	v_mul_f32_e32 v21, 0xbfb8aa3b, v17
	v_mul_f32_e32 v22, 0xbfb8aa3b, v18
	v_mul_f32_e32 v23, 0xbfb8aa3b, v19
	v_exp_f32_e32 v20, v20
	v_exp_f32_e32 v21, v21
	v_exp_f32_e32 v22, v22
	v_exp_f32_e32 v23, v23
	s_nop 0
	v_add_f32_e32 v20, 1.0, v20
	v_add_f32_e32 v21, 1.0, v21
	v_add_f32_e32 v22, 1.0, v22
	v_add_f32_e32 v23, 1.0, v23
	v_div_scale_f32 v8, s[0:1], v20, v20, v16
	v_rcp_f32_e32 v9, v8
	s_nop 0
	v_fma_f32 v10, -v8, v9, 1.0
	v_fmac_f32_e32 v9, v10, v9
	v_div_scale_f32 v10, vcc, v16, v20, v16
	v_mul_f32_e32 v11, v10, v9
	v_fma_f32 v12, -v8, v11, v10
	v_fmac_f32_e32 v11, v12, v9
	v_fma_f32 v8, -v8, v11, v10
	v_div_fmas_f32 v8, v8, v9, v11
	v_div_fixup_f32 v24, v8, v20, v16
	v_div_scale_f32 v8, s[0:1], v21, v21, v17
	v_rcp_f32_e32 v9, v8
	s_nop 0
	v_fma_f32 v10, -v8, v9, 1.0
	v_fmac_f32_e32 v9, v10, v9
	v_div_scale_f32 v10, vcc, v17, v21, v17
	v_mul_f32_e32 v11, v10, v9
	v_fma_f32 v12, -v8, v11, v10
	v_fmac_f32_e32 v11, v12, v9
	v_fma_f32 v8, -v8, v11, v10
	v_div_fmas_f32 v8, v8, v9, v11
	v_div_fixup_f32 v25, v8, v21, v17
	v_div_scale_f32 v8, s[0:1], v22, v22, v18
	v_rcp_f32_e32 v9, v8
	s_nop 0
	v_fma_f32 v10, -v8, v9, 1.0
	v_fmac_f32_e32 v9, v10, v9
	v_div_scale_f32 v10, vcc, v18, v22, v18
	v_mul_f32_e32 v11, v10, v9
	v_fma_f32 v12, -v8, v11, v10
	v_fmac_f32_e32 v11, v12, v9
	v_fma_f32 v8, -v8, v11, v10
	v_div_fmas_f32 v8, v8, v9, v11
	v_div_fixup_f32 v26, v8, v22, v18
	v_div_scale_f32 v8, s[0:1], v23, v23, v19
	v_rcp_f32_e32 v9, v8
	s_nop 0
	v_fma_f32 v10, -v8, v9, 1.0
	v_fmac_f32_e32 v9, v10, v9
	v_div_scale_f32 v10, vcc, v19, v23, v19
	v_mul_f32_e32 v11, v10, v9
	v_fma_f32 v12, -v8, v11, v10
	v_fmac_f32_e32 v11, v12, v9
	v_fma_f32 v8, -v8, v11, v10
	v_div_fmas_f32 v8, v8, v9, v11
	v_div_fixup_f32 v27, v8, v23, v19
	v_mul_f32_e32 v24, v24, v60
	v_mul_f32_e32 v25, v25, v61
	v_mul_f32_e32 v26, v26, v62
	v_mul_f32_e32 v27, v27, v63
	v_mul_f32_e32 v24, v24, v6
	v_mul_f32_e32 v25, v25, v6
	v_mul_f32_e32 v26, v26, v6
	v_mul_f32_e32 v27, v27, v6
	v_cvt_pk_bf16_f32 v30, v24, v25
	v_cvt_pk_bf16_f32 v31, v26, v27
	global_store_dwordx2 v2, v[30:31], s[88:89] offset:112
	s_add_i32 s2, s2, s71
	v_readlane_b32 s0, v206, 49
	s_nop 0
	s_cmp_ge_u32 s2, s0
	s_cbranch_scc0 .LBB0_350
	s_branch .LBB0_343
